# RESID epilogue: the 16 residual-stream loads and their address arithmetic issued before the leading half's end-of-unit barrier
# baseline (speedup 1.0000x reference)
; #define PG8_STAGE(bufoff, gbase, voff) do { _Pragma("unroll") for (int _i = 0; _i < 2; ++_i) \
;         __builtin_amdgcn_global_load_lds((const unsigned*)((const char*)(gbase) + (voff)[_i]), (PG8_LAS unsigned*)(lds + (bufoff) + ldsw + _i * 8192), 16, 0, 0); } while (0)
; #define PG8_LDA(dst, b, h) do { _Pragma("unroll") for (int m = 0; m < 4; ++m) _Pragma("unroll") for (int k = 0; k < 2; ++k) dst[m][k] = *(const PG8_LAS bf16x8*)(lds + PG8_SA(b, h) + aoff + m * 2048 + k * 1024); } while (0)
; #define PG8_LDB(dst, b, h) do { _Pragma("unroll") for (int n = 0; n < 2; ++n) _Pragma("unroll") for (int k = 0; k < 2; ++k) dst[n][k] = *(const PG8_LAS bf16x8*)(lds + PG8_SB(b, h) + boff + n * 2048 + k * 1024); } while (0)
; #define PG8_MMA(ai, bj, At, Bt) do { __builtin_amdgcn_s_setprio(1); _Pragma("unroll") for (int m = 0; m < 4; ++m) _Pragma("unroll") for (int n = 0; n < 2; ++n) _Pragma("unroll") for (int k = 0; k < 2; ++k) \
;         acc[ai][bj][m][n] = __builtin_amdgcn_mfma_f32_16x16x32_bf16(Bt[n][k], At[m][k], acc[ai][bj][m][n], 0, 0, 0); __builtin_amdgcn_s_setprio(0); } while (0)
; #define PG8_WAIT_V(n) asm volatile("s_waitcnt vmcnt(" #n ")" ::: "memory")
; #define PG8_WAIT_L(n) asm volatile("s_waitcnt lgkmcnt(" #n ")" ::: "memory")
; #define PG8_BAR __builtin_amdgcn_s_barrier()
; #define PG8_SCHED __builtin_amdgcn_sched_barrier(0)
; template <class Epi, class Sched, bool ALIGN_EPI = false, bool SP2 = false>
; __device__ __forceinline__ void gemm_phase(PG8_LAS unsigned char* lds, const Gemm g, const Sched& S, const Epi& E) {
;     ...
;             PG8_LDB(B0, 0, 0); PG8_LDB(B1, 0, 1); PG8_SCHED; PG8_LDA(At, 0, 0); PG8_STAGE(PG8_SA(1, 1), a1 + hstepA, voffA);
;             PG8_WAIT_V(8); PG8_WAIT_L(0); PG8_BAR; PG8_MMA(0, 0, At, B0); PG8_MMA(0, 1, At, B1); PG8_BAR; PG8_SCHED;
;             PG8_LDA(At, 0, 1); PG8_STAGE(PG8_SB(0, 0), b2, voffB); PG8_STAGE(PG8_SB(0, 1), b2 + hstep, voffB); PG8_STAGE(PG8_SA(0, 0), a2, voffA);
;             PG8_WAIT_V(8); PG8_WAIT_L(0); PG8_BAR; PG8_MMA(1, 0, At, B0); PG8_MMA(1, 1, At, B1); PG8_BAR; PG8_SCHED;
.LBB0_600:
	s_add_i32 s66, s48, 2
	s_add_u32 s67, s46, 0x80
	s_addc_u32 s49, s47, 0
	s_add_i32 s70, 0, 0x10000
	s_cmp_eq_u32 s62, s48
	s_cselect_b32 s49, s7, s49
	s_cselect_b32 s48, s6, s67
	s_cselect_b32 s69, s21, s19
	s_cselect_b32 s68, s20, s5
	s_add_i32 s67, 0, 0x14000
	v_add_u32_e32 v140, s70, v243
	v_add_u32_e32 v156, s67, v243
	ds_read_b128 v[120:123], v140
	ds_read_b128 v[132:135], v140 offset:1024
	ds_read_b128 v[136:139], v140 offset:2048
	ds_read_b128 v[140:143], v140 offset:3072
	ds_read_b128 v[144:147], v156
	ds_read_b128 v[148:151], v156 offset:1024
	ds_read_b128 v[152:155], v156 offset:2048
	ds_read_b128 v[156:159], v156 offset:3072
	v_lshl_add_u64 v[212:213], s[46:47], 0, v[204:205]
	s_add_i32 m0, s55, 0xc000
	ds_read_b128 v[160:163], v247
	ds_read_b128 v[164:167], v247 offset:1024
	ds_read_b128 v[168:171], v247 offset:2048
	ds_read_b128 v[176:179], v247 offset:3072
	ds_read_b128 v[184:187], v247 offset:4096
	ds_read_b128 v[188:191], v247 offset:5120
	ds_read_b128 v[192:195], v247 offset:6144
	ds_read_b128 v[208:211], v247 offset:7168
	global_load_lds_dwordx4 v[212:213], off
	v_lshl_add_u64 v[212:213], s[46:47], 0, v[206:207]
	s_add_i32 m0, s55, 0xe000
	s_nop 0
	global_load_lds_dwordx4 v[212:213], off
	s_waitcnt vmcnt(8)
	s_waitcnt lgkmcnt(0)
	s_barrier
	s_setprio 1
	s_waitcnt lgkmcnt(0)
	v_mfma_f32_16x16x32_bf16 v[180:183], v[120:123], v[160:163], v[180:183]
	v_mfma_f32_16x16x32_bf16 v[172:175], v[136:139], v[160:163], v[172:175]
	v_mfma_f32_16x16x32_bf16 v[116:119], v[120:123], v[168:171], v[116:119]
	v_mfma_f32_16x16x32_bf16 v[112:115], v[136:139], v[168:171], v[112:115]
	v_mfma_f32_16x16x32_bf16 v[100:103], v[120:123], v[184:187], v[100:103]
	v_mfma_f32_16x16x32_bf16 v[96:99], v[136:139], v[184:187], v[96:99]
	v_mfma_f32_16x16x32_bf16 v[84:87], v[120:123], v[192:195], v[84:87]
	v_mfma_f32_16x16x32_bf16 v[74:77], v[136:139], v[192:195], v[74:77]
	v_mfma_f32_16x16x32_bf16 v[180:183], v[132:135], v[164:167], v[180:183]
	v_mfma_f32_16x16x32_bf16 v[172:175], v[140:143], v[164:167], v[172:175]
	v_mfma_f32_16x16x32_bf16 v[116:119], v[132:135], v[176:179], v[116:119]
	v_mfma_f32_16x16x32_bf16 v[112:115], v[140:143], v[176:179], v[112:115]
	v_mfma_f32_16x16x32_bf16 v[100:103], v[132:135], v[188:191], v[100:103]
	v_mfma_f32_16x16x32_bf16 v[96:99], v[140:143], v[188:191], v[96:99]
	v_mfma_f32_16x16x32_bf16 v[84:87], v[132:135], v[208:211], v[84:87]
	v_mfma_f32_16x16x32_bf16 v[74:77], v[140:143], v[208:211], v[74:77]
	v_mfma_f32_16x16x32_bf16 v[128:131], v[144:147], v[160:163], v[128:131]
	v_mfma_f32_16x16x32_bf16 v[124:127], v[152:155], v[160:163], v[124:127]
	v_mfma_f32_16x16x32_bf16 v[108:111], v[144:147], v[168:171], v[108:111]
	v_mfma_f32_16x16x32_bf16 v[104:107], v[152:155], v[168:171], v[104:107]
	v_mfma_f32_16x16x32_bf16 v[92:95], v[144:147], v[184:187], v[92:95]
	v_mfma_f32_16x16x32_bf16 v[88:91], v[152:155], v[184:187], v[88:91]
	v_mfma_f32_16x16x32_bf16 v[70:73], v[144:147], v[192:195], v[70:73]
	v_mfma_f32_16x16x32_bf16 v[66:69], v[152:155], v[192:195], v[66:69]
	v_mfma_f32_16x16x32_bf16 v[128:131], v[148:151], v[164:167], v[128:131]
	v_mfma_f32_16x16x32_bf16 v[124:127], v[156:159], v[164:167], v[124:127]
	v_mfma_f32_16x16x32_bf16 v[108:111], v[148:151], v[176:179], v[108:111]
	v_mfma_f32_16x16x32_bf16 v[104:107], v[156:159], v[176:179], v[104:107]
	v_mfma_f32_16x16x32_bf16 v[92:95], v[148:151], v[188:191], v[92:95]
	v_mfma_f32_16x16x32_bf16 v[88:91], v[156:159], v[188:191], v[88:91]
	v_mfma_f32_16x16x32_bf16 v[70:73], v[148:151], v[208:211], v[70:73]
	v_mfma_f32_16x16x32_bf16 v[66:69], v[156:159], v[208:211], v[66:69]
	s_setprio 0
	s_barrier
	s_add_i32 s70, s70, s54
	v_lshl_add_u64 v[212:213], s[68:69], 0, v[200:201]
	s_mov_b32 m0, s70
	ds_read_b128 v[160:163], v247 offset:16384
	ds_read_b128 v[164:167], v247 offset:17408
	ds_read_b128 v[168:171], v247 offset:18432
	ds_read_b128 v[176:179], v247 offset:19456
	ds_read_b128 v[184:187], v247 offset:20480
	ds_read_b128 v[188:191], v247 offset:21504
	ds_read_b128 v[192:195], v247 offset:22528
	ds_read_b128 v[208:211], v247 offset:23552
	global_load_lds_dwordx4 v[212:213], off
	s_add_i32 m0, s70, 0x2000
	v_lshl_add_u64 v[214:215], s[68:69], 0, v[78:79]
	s_add_u32 s68, s68, s25
	s_addc_u32 s69, s69, 0
	s_add_i32 s67, s67, s54
	global_load_lds_dwordx4 v[214:215], off
	v_lshl_add_u64 v[216:217], s[68:69], 0, v[200:201]
	s_mov_b32 m0, s67
	v_lshl_add_u64 v[218:219], s[68:69], 0, v[78:79]
	global_load_lds_dwordx4 v[216:217], off
	s_add_i32 m0, s67, 0x2000
	v_lshl_add_u64 v[220:221], s[48:49], 0, v[202:203]
	global_load_lds_dwordx4 v[218:219], off
	s_mov_b32 m0, s55
	v_lshl_add_u64 v[222:223], s[48:49], 0, v[198:199]
	global_load_lds_dwordx4 v[220:221], off
	s_mov_b32 m0, s56
	s_nop 0
	global_load_lds_dwordx4 v[222:223], off
	s_waitcnt vmcnt(8)
	s_waitcnt lgkmcnt(0)
	s_barrier
; #define PG8_STAGE(bufoff, gbase, voff) do { _Pragma("unroll") for (int _i = 0; _i < 2; ++_i) \
;         __builtin_amdgcn_global_load_lds((const unsigned*)((const char*)(gbase) + (voff)[_i]), (PG8_LAS unsigned*)(lds + (bufoff) + ldsw + _i * 8192), 16, 0, 0); } while (0)
; #define PG8_LDA(dst, b, h) do { _Pragma("unroll") for (int m = 0; m < 4; ++m) _Pragma("unroll") for (int k = 0; k < 2; ++k) dst[m][k] = *(const PG8_LAS bf16x8*)(lds + PG8_SA(b, h) + aoff + m * 2048 + k * 1024); } while (0)
; #define PG8_LDB(dst, b, h) do { _Pragma("unroll") for (int n = 0; n < 2; ++n) _Pragma("unroll") for (int k = 0; k < 2; ++k) dst[n][k] = *(const PG8_LAS bf16x8*)(lds + PG8_SB(b, h) + boff + n * 2048 + k * 1024); } while (0)
; #define PG8_MMA(ai, bj, At, Bt) do { __builtin_amdgcn_s_setprio(1); _Pragma("unroll") for (int m = 0; m < 4; ++m) _Pragma("unroll") for (int n = 0; n < 2; ++n) _Pragma("unroll") for (int k = 0; k < 2; ++k) \
;         acc[ai][bj][m][n] = __builtin_amdgcn_mfma_f32_16x16x32_bf16(Bt[n][k], At[m][k], acc[ai][bj][m][n], 0, 0, 0); __builtin_amdgcn_s_setprio(0); } while (0)
; #define PG8_WAIT_V(n) asm volatile("s_waitcnt vmcnt(" #n ")" ::: "memory")
; #define PG8_WAIT_L(n) asm volatile("s_waitcnt lgkmcnt(" #n ")" ::: "memory")
; #define PG8_BAR __builtin_amdgcn_s_barrier()
; #define PG8_SCHED __builtin_amdgcn_sched_barrier(0)
; template <class Epi, class Sched, bool ALIGN_EPI = false, bool SP2 = false>
; __device__ __forceinline__ void gemm_phase(PG8_LAS unsigned char* lds, const Gemm g, const Sched& S, const Epi& E) {
;     ...
;             PG8_WAIT_V(8); PG8_WAIT_L(0); PG8_BAR; PG8_MMA(1, 0, At, B0); PG8_MMA(1, 1, At, B1); PG8_BAR; PG8_SCHED;
;             PG8_LDB(B0, 1, 0); PG8_LDB(B1, 1, 1); PG8_SCHED; PG8_LDA(At, 1, 0); PG8_STAGE(PG8_SA(0, 1), a2 + hstepA, voffA);
;             PG8_WAIT_V(8); PG8_WAIT_L(0); PG8_BAR; PG8_MMA(0, 0, At, B0); PG8_MMA(0, 1, At, B1); PG8_BAR; PG8_SCHED;
;             PG8_LDA(At, 1, 1); PG8_STAGE(PG8_SB(1, 0), b3, voffB); PG8_STAGE(PG8_SB(1, 1), b3 + hstep, voffB); PG8_STAGE(PG8_SA(1, 0), a3, voffA);
	s_setprio 1
	s_waitcnt lgkmcnt(0)
	v_mfma_f32_16x16x32_bf16 v[62:65], v[120:123], v[160:163], v[62:65]
	v_mfma_f32_16x16x32_bf16 v[58:61], v[136:139], v[160:163], v[58:61]
	v_mfma_f32_16x16x32_bf16 v[46:49], v[120:123], v[168:171], v[46:49]
	v_mfma_f32_16x16x32_bf16 v[42:45], v[136:139], v[168:171], v[42:45]
	v_mfma_f32_16x16x32_bf16 v[30:33], v[120:123], v[184:187], v[30:33]
	v_mfma_f32_16x16x32_bf16 v[26:29], v[136:139], v[184:187], v[26:29]
	v_mfma_f32_16x16x32_bf16 v[14:17], v[120:123], v[192:195], v[14:17]
	v_mfma_f32_16x16x32_bf16 v[10:13], v[136:139], v[192:195], v[10:13]
	v_mfma_f32_16x16x32_bf16 v[62:65], v[132:135], v[164:167], v[62:65]
	v_mfma_f32_16x16x32_bf16 v[58:61], v[140:143], v[164:167], v[58:61]
	v_mfma_f32_16x16x32_bf16 v[46:49], v[132:135], v[176:179], v[46:49]
	v_mfma_f32_16x16x32_bf16 v[42:45], v[140:143], v[176:179], v[42:45]
	v_mfma_f32_16x16x32_bf16 v[30:33], v[132:135], v[188:191], v[30:33]
	v_mfma_f32_16x16x32_bf16 v[26:29], v[140:143], v[188:191], v[26:29]
	v_mfma_f32_16x16x32_bf16 v[14:17], v[132:135], v[208:211], v[14:17]
	v_mfma_f32_16x16x32_bf16 v[10:13], v[140:143], v[208:211], v[10:13]
	v_mfma_f32_16x16x32_bf16 v[54:57], v[144:147], v[160:163], v[54:57]
	v_mfma_f32_16x16x32_bf16 v[50:53], v[152:155], v[160:163], v[50:53]
	v_mfma_f32_16x16x32_bf16 v[38:41], v[144:147], v[168:171], v[38:41]
	v_mfma_f32_16x16x32_bf16 v[34:37], v[152:155], v[168:171], v[34:37]
	v_mfma_f32_16x16x32_bf16 v[22:25], v[144:147], v[184:187], v[22:25]
	v_mfma_f32_16x16x32_bf16 v[18:21], v[152:155], v[184:187], v[18:21]
	v_mfma_f32_16x16x32_bf16 v[6:9], v[144:147], v[192:195], v[6:9]
	v_mfma_f32_16x16x32_bf16 v[2:5], v[152:155], v[192:195], v[2:5]
	v_mfma_f32_16x16x32_bf16 v[54:57], v[148:151], v[164:167], v[54:57]
	v_mfma_f32_16x16x32_bf16 v[50:53], v[156:159], v[164:167], v[50:53]
	v_mfma_f32_16x16x32_bf16 v[38:41], v[148:151], v[176:179], v[38:41]
	v_mfma_f32_16x16x32_bf16 v[34:37], v[156:159], v[176:179], v[34:37]
	v_mfma_f32_16x16x32_bf16 v[22:25], v[148:151], v[188:191], v[22:25]
	v_mfma_f32_16x16x32_bf16 v[18:21], v[156:159], v[188:191], v[18:21]
	v_mfma_f32_16x16x32_bf16 v[6:9], v[148:151], v[208:211], v[6:9]
	v_mfma_f32_16x16x32_bf16 v[2:5], v[156:159], v[208:211], v[2:5]
	s_setprio 0
	s_barrier
	s_add_i32 s67, 0, 0x18000
	s_add_i32 s68, 0, 0x1c000
	v_add_u32_e32 v140, s67, v243
	v_add_u32_e32 v156, s68, v243
	ds_read_b128 v[120:123], v140
	ds_read_b128 v[132:135], v140 offset:1024
	ds_read_b128 v[136:139], v140 offset:2048
	ds_read_b128 v[140:143], v140 offset:3072
	ds_read_b128 v[144:147], v156
	ds_read_b128 v[148:151], v156 offset:1024
	ds_read_b128 v[152:155], v156 offset:2048
	ds_read_b128 v[156:159], v156 offset:3072
	s_add_u32 s48, s48, s0
	s_addc_u32 s49, s49, 0
	s_mov_b32 m0, s57
	v_lshl_add_u64 v[224:225], s[48:49], 0, v[202:203]
	ds_read_b128 v[160:163], v247 offset:32768
	ds_read_b128 v[164:167], v247 offset:33792
	ds_read_b128 v[168:171], v247 offset:34816
	ds_read_b128 v[176:179], v247 offset:35840
	ds_read_b128 v[184:187], v247 offset:36864
	ds_read_b128 v[188:191], v247 offset:37888
	ds_read_b128 v[192:195], v247 offset:38912
	ds_read_b128 v[208:211], v247 offset:39936
	global_load_lds_dwordx4 v[224:225], off
	v_lshl_add_u64 v[224:225], s[48:49], 0, v[198:199]
	s_mov_b32 m0, s58
	s_nop 0
	global_load_lds_dwordx4 v[224:225], off
	s_waitcnt vmcnt(8)
	s_waitcnt lgkmcnt(0)
	s_barrier
	s_setprio 1
	s_waitcnt lgkmcnt(0)
	v_mfma_f32_16x16x32_bf16 v[180:183], v[120:123], v[160:163], v[180:183]
	v_mfma_f32_16x16x32_bf16 v[172:175], v[136:139], v[160:163], v[172:175]
	v_mfma_f32_16x16x32_bf16 v[116:119], v[120:123], v[168:171], v[116:119]
	v_mfma_f32_16x16x32_bf16 v[112:115], v[136:139], v[168:171], v[112:115]
	v_mfma_f32_16x16x32_bf16 v[100:103], v[120:123], v[184:187], v[100:103]
	v_mfma_f32_16x16x32_bf16 v[96:99], v[136:139], v[184:187], v[96:99]
	v_mfma_f32_16x16x32_bf16 v[84:87], v[120:123], v[192:195], v[84:87]
	v_mfma_f32_16x16x32_bf16 v[74:77], v[136:139], v[192:195], v[74:77]
	v_mfma_f32_16x16x32_bf16 v[180:183], v[132:135], v[164:167], v[180:183]
	v_mfma_f32_16x16x32_bf16 v[172:175], v[140:143], v[164:167], v[172:175]
	v_mfma_f32_16x16x32_bf16 v[116:119], v[132:135], v[176:179], v[116:119]
	v_mfma_f32_16x16x32_bf16 v[112:115], v[140:143], v[176:179], v[112:115]
	v_mfma_f32_16x16x32_bf16 v[100:103], v[132:135], v[188:191], v[100:103]
	v_mfma_f32_16x16x32_bf16 v[96:99], v[140:143], v[188:191], v[96:99]
	v_mfma_f32_16x16x32_bf16 v[84:87], v[132:135], v[208:211], v[84:87]
	v_mfma_f32_16x16x32_bf16 v[74:77], v[140:143], v[208:211], v[74:77]
	v_mfma_f32_16x16x32_bf16 v[128:131], v[144:147], v[160:163], v[128:131]
	v_mfma_f32_16x16x32_bf16 v[124:127], v[152:155], v[160:163], v[124:127]
	v_mfma_f32_16x16x32_bf16 v[108:111], v[144:147], v[168:171], v[108:111]
	v_mfma_f32_16x16x32_bf16 v[104:107], v[152:155], v[168:171], v[104:107]
	v_mfma_f32_16x16x32_bf16 v[92:95], v[144:147], v[184:187], v[92:95]
	v_mfma_f32_16x16x32_bf16 v[88:91], v[152:155], v[184:187], v[88:91]
	v_mfma_f32_16x16x32_bf16 v[70:73], v[144:147], v[192:195], v[70:73]
	v_mfma_f32_16x16x32_bf16 v[66:69], v[152:155], v[192:195], v[66:69]
	v_mfma_f32_16x16x32_bf16 v[128:131], v[148:151], v[164:167], v[128:131]
	v_mfma_f32_16x16x32_bf16 v[124:127], v[156:159], v[164:167], v[124:127]
	v_mfma_f32_16x16x32_bf16 v[108:111], v[148:151], v[176:179], v[108:111]
	v_mfma_f32_16x16x32_bf16 v[104:107], v[156:159], v[176:179], v[104:107]
	v_mfma_f32_16x16x32_bf16 v[92:95], v[148:151], v[188:191], v[92:95]
	v_mfma_f32_16x16x32_bf16 v[88:91], v[156:159], v[188:191], v[88:91]
	v_mfma_f32_16x16x32_bf16 v[70:73], v[148:151], v[208:211], v[70:73]
	v_mfma_f32_16x16x32_bf16 v[66:69], v[156:159], v[208:211], v[66:69]
	s_setprio 0
	s_barrier
; #define PG8_STAGE(bufoff, gbase, voff) do { _Pragma("unroll") for (int _i = 0; _i < 2; ++_i) \
;         __builtin_amdgcn_global_load_lds((const unsigned*)((const char*)(gbase) + (voff)[_i]), (PG8_LAS unsigned*)(lds + (bufoff) + ldsw + _i * 8192), 16, 0, 0); } while (0)
; #define PG8_LDA(dst, b, h) do { _Pragma("unroll") for (int m = 0; m < 4; ++m) _Pragma("unroll") for (int k = 0; k < 2; ++k) dst[m][k] = *(const PG8_LAS bf16x8*)(lds + PG8_SA(b, h) + aoff + m * 2048 + k * 1024); } while (0)
; #define PG8_MMA(ai, bj, At, Bt) do { __builtin_amdgcn_s_setprio(1); _Pragma("unroll") for (int m = 0; m < 4; ++m) _Pragma("unroll") for (int n = 0; n < 2; ++n) _Pragma("unroll") for (int k = 0; k < 2; ++k) \
;         acc[ai][bj][m][n] = __builtin_amdgcn_mfma_f32_16x16x32_bf16(Bt[n][k], At[m][k], acc[ai][bj][m][n], 0, 0, 0); __builtin_amdgcn_s_setprio(0); } while (0)
; #define PG8_WAIT_V(n) asm volatile("s_waitcnt vmcnt(" #n ")" ::: "memory")
; #define PG8_WAIT_L(n) asm volatile("s_waitcnt lgkmcnt(" #n ")" ::: "memory")
; #define PG8_BAR __builtin_amdgcn_s_barrier()
; #define PG8_SCHED __builtin_amdgcn_sched_barrier(0)
;     __device__ __forceinline__ void operator()(const f32x4 (&acc)[2][2][4][2], const Unit& u, int wr, int wc, int fr, int fq) const {
;         const int row0 = u.pm * BM + wr * 64 + fr; const int col0 = u.pn * BM + wc * 32 + 8 * fq;
;         u32x4 hv[2][4][2];
; #pragma unroll
;         for (int ai = 0; ai < 2; ++ai)
; #pragma unroll
;             for (int m = 0; m < 4; ++m)
; #pragma unroll
;                 for (int bj = 0; bj < 2; ++bj) hv[ai][m][bj] = *(const u32x4*)(HB + (size_t)(row0 + ai * HALF + m * 16) * 1024 + col0 + bj * HALF);
; template <class Epi, class Sched, bool ALIGN_EPI = false, bool SP2 = false>
; __device__ __forceinline__ void gemm_phase(PG8_LAS unsigned char* lds, const Gemm g, const Sched& S, const Epi& E) {
;     ...
;             PG8_LDA(At, 1, 1); PG8_STAGE(PG8_SB(1, 0), b3, voffB); PG8_STAGE(PG8_SB(1, 1), b3 + hstep, voffB); PG8_STAGE(PG8_SA(1, 0), a3, voffA);
;             PG8_WAIT_V(8); PG8_WAIT_L(0); PG8_BAR; PG8_MMA(1, 0, At, B0); PG8_MMA(1, 1, At, B1); PG8_BAR; PG8_SCHED;
	s_add_i32 s48, s67, s54
	v_lshl_add_u64 v[212:213], v[212:213], 0, s[26:27]
	s_mov_b32 m0, s48
	ds_read_b128 v[160:163], v247 offset:49152
	ds_read_b128 v[164:167], v247 offset:50176
	ds_read_b128 v[168:171], v247 offset:51200
	ds_read_b128 v[176:179], v247 offset:52224
	ds_read_b128 v[184:187], v247 offset:53248
	ds_read_b128 v[188:191], v247 offset:54272
	ds_read_b128 v[192:195], v247 offset:55296
	ds_read_b128 v[208:211], v247 offset:56320
	global_load_lds_dwordx4 v[212:213], off
	v_lshl_add_u64 v[212:213], v[214:215], 0, s[26:27]
	s_add_i32 m0, s48, 0x2000
	s_add_i32 s48, s68, s54
	global_load_lds_dwordx4 v[212:213], off
	v_lshl_add_u64 v[212:213], v[216:217], 0, s[26:27]
	s_mov_b32 m0, s48
	s_nop 0
	global_load_lds_dwordx4 v[212:213], off
	v_lshl_add_u64 v[212:213], v[218:219], 0, s[26:27]
	s_add_i32 m0, s48, 0x2000
	s_nop 0
	global_load_lds_dwordx4 v[212:213], off
	v_lshl_add_u64 v[212:213], v[220:221], 0, s[26:27]
	s_mov_b32 m0, s59
	s_nop 0
	global_load_lds_dwordx4 v[212:213], off
	v_lshl_add_u64 v[212:213], v[222:223], 0, s[26:27]
	s_mov_b32 m0, s60
	s_nop 0
	global_load_lds_dwordx4 v[212:213], off
	s_waitcnt vmcnt(8)
	s_waitcnt lgkmcnt(0)
	s_barrier
	s_setprio 1
	s_waitcnt lgkmcnt(0)
	v_mfma_f32_16x16x32_bf16 v[62:65], v[120:123], v[160:163], v[62:65]
	v_mfma_f32_16x16x32_bf16 v[58:61], v[136:139], v[160:163], v[58:61]
	v_mfma_f32_16x16x32_bf16 v[46:49], v[120:123], v[168:171], v[46:49]
	v_mfma_f32_16x16x32_bf16 v[42:45], v[136:139], v[168:171], v[42:45]
	v_mfma_f32_16x16x32_bf16 v[30:33], v[120:123], v[184:187], v[30:33]
	v_mfma_f32_16x16x32_bf16 v[26:29], v[136:139], v[184:187], v[26:29]
	v_mfma_f32_16x16x32_bf16 v[14:17], v[120:123], v[192:195], v[14:17]
	v_mfma_f32_16x16x32_bf16 v[10:13], v[136:139], v[192:195], v[10:13]
	v_mfma_f32_16x16x32_bf16 v[62:65], v[132:135], v[164:167], v[62:65]
	v_mfma_f32_16x16x32_bf16 v[58:61], v[140:143], v[164:167], v[58:61]
	v_mfma_f32_16x16x32_bf16 v[46:49], v[132:135], v[176:179], v[46:49]
	v_mfma_f32_16x16x32_bf16 v[42:45], v[140:143], v[176:179], v[42:45]
	v_mfma_f32_16x16x32_bf16 v[30:33], v[132:135], v[188:191], v[30:33]
	v_mfma_f32_16x16x32_bf16 v[26:29], v[140:143], v[188:191], v[26:29]
	v_mfma_f32_16x16x32_bf16 v[14:17], v[132:135], v[208:211], v[14:17]
	v_mfma_f32_16x16x32_bf16 v[10:13], v[140:143], v[208:211], v[10:13]
	v_mfma_f32_16x16x32_bf16 v[54:57], v[144:147], v[160:163], v[54:57]
	v_mfma_f32_16x16x32_bf16 v[50:53], v[152:155], v[160:163], v[50:53]
	v_mfma_f32_16x16x32_bf16 v[38:41], v[144:147], v[168:171], v[38:41]
	v_mfma_f32_16x16x32_bf16 v[34:37], v[152:155], v[168:171], v[34:37]
	v_mfma_f32_16x16x32_bf16 v[22:25], v[144:147], v[184:187], v[22:25]
	v_mfma_f32_16x16x32_bf16 v[18:21], v[152:155], v[184:187], v[18:21]
	v_mfma_f32_16x16x32_bf16 v[6:9], v[144:147], v[192:195], v[6:9]
	v_mfma_f32_16x16x32_bf16 v[2:5], v[152:155], v[192:195], v[2:5]
	v_mfma_f32_16x16x32_bf16 v[54:57], v[148:151], v[164:167], v[54:57]
	v_mfma_f32_16x16x32_bf16 v[50:53], v[156:159], v[164:167], v[50:53]
	v_mfma_f32_16x16x32_bf16 v[38:41], v[148:151], v[176:179], v[38:41]
	v_mfma_f32_16x16x32_bf16 v[34:37], v[156:159], v[176:179], v[34:37]
	v_mfma_f32_16x16x32_bf16 v[22:25], v[148:151], v[188:191], v[22:25]
	v_mfma_f32_16x16x32_bf16 v[18:21], v[156:159], v[188:191], v[18:21]
	v_mfma_f32_16x16x32_bf16 v[6:9], v[148:151], v[208:211], v[6:9]
	v_mfma_f32_16x16x32_bf16 v[2:5], v[156:159], v[208:211], v[2:5]
	s_setprio 0
	s_barrier
	s_add_u32 s46, s46, 0x100
	s_addc_u32 s47, s47, 0
	s_add_u32 s5, s5, 0x100
	s_addc_u32 s19, s19, 0
	s_cmp_ge_u32 s66, s61
	s_mov_b32 s48, s66
	s_cbranch_scc0 .LBB0_600
	s_lshl_b32 s4, s4, 8
	v_lshl_or_b32 v208, s18, 8, v244
	v_add_u32_e32 v120, s4, v1
	v_ashrrev_i32_e32 v209, 31, v208
	v_lshlrev_b64 v[224:225], 1, v[208:209]
	v_ashrrev_i32_e32 v121, 31, v120
	v_lshl_add_u64 v[122:123], s[30:31], 0, v[224:225]
	v_lshlrev_b64 v[226:227], 11, v[120:121]
	v_lshl_add_u64 v[132:133], v[122:123], 0, v[226:227]
	global_load_dwordx4 v[236:239], v[132:133], off
	global_load_dwordx4 v[192:195], v[132:133], off offset:256
	v_or_b32_e32 v132, 16, v120
	v_ashrrev_i32_e32 v133, 31, v132
	v_lshlrev_b64 v[222:223], 11, v[132:133]
	v_lshl_add_u64 v[132:133], v[122:123], 0, v[222:223]
	global_load_dwordx4 v[188:191], v[132:133], off
	global_load_dwordx4 v[184:187], v[132:133], off offset:256
	v_or_b32_e32 v132, 32, v120
	v_or_b32_e32 v120, 48, v120
	v_ashrrev_i32_e32 v133, 31, v132
	v_ashrrev_i32_e32 v121, 31, v120
	v_lshlrev_b64 v[220:221], 11, v[132:133]
	v_lshlrev_b64 v[218:219], 11, v[120:121]
	v_lshl_add_u64 v[132:133], v[122:123], 0, v[220:221]
	v_lshl_add_u64 v[120:121], v[122:123], 0, v[218:219]
	v_lshl_add_u64 v[216:217], v[226:227], 0, s[38:39]
	s_mov_b64 s[46:47], 0x48000
	global_load_dwordx4 v[176:179], v[132:133], off
	global_load_dwordx4 v[168:171], v[132:133], off offset:256
	global_load_dwordx4 v[164:167], v[120:121], off
	global_load_dwordx4 v[160:163], v[120:121], off offset:256
	v_lshl_add_u64 v[120:121], v[122:123], 0, v[216:217]
	v_lshl_add_u64 v[214:215], v[226:227], 0, s[46:47]
	s_mov_b64 s[46:47], 0x50000
	global_load_dwordx4 v[156:159], v[120:121], off
	global_load_dwordx4 v[148:151], v[120:121], off offset:256
	v_lshl_add_u64 v[120:121], v[122:123], 0, v[214:215]
	v_lshl_add_u64 v[212:213], v[226:227], 0, s[46:47]
	s_mov_b64 s[46:47], 0x58000
	global_load_dwordx4 v[152:155], v[120:121], off
	global_load_dwordx4 v[144:147], v[120:121], off offset:256
	v_lshl_add_u64 v[120:121], v[122:123], 0, v[212:213]
	v_lshl_add_u64 v[210:211], v[226:227], 0, s[46:47]
	global_load_dwordx4 v[140:143], v[120:121], off
	global_load_dwordx4 v[136:139], v[120:121], off offset:256
	v_lshl_add_u64 v[120:121], v[122:123], 0, v[210:211]
	global_load_dwordx4 v[132:135], v[120:121], off
	s_nop 0
	global_load_dwordx4 v[120:123], v[120:121], off offset:256
	s_and_b64 vcc, exec, s[10:11]
	s_cbranch_vccz .LBB0_603
	s_barrier
; __device__ __forceinline__ unsigned cvt_pk_bf16(float lo, float hi) { unsigned r; asm volatile("v_cvt_pk_bf16_f32 %0, %1, %2" : "=v"(r) : "v"(lo), "v"(hi)); return r; }
;     __device__ __forceinline__ void operator()(const f32x4 (&acc)[2][2][4][2], const Unit& u, int wr, int wc, int fr, int fq) const {
;     ...
;             for (int m = 0; m < 4; ++m) { const size_t off = (size_t)(row0 + ai * HALF + m * 16) * 1024 + col0; float s = 0.f;
; #pragma unroll
;                 for (int bj = 0; bj < 2; ++bj) { const unsigned hq[4] = {hv[ai][m][bj].x, hv[ai][m][bj].y, hv[ai][m][bj].z, hv[ai][m][bj].w}; unsigned wq[4];
; #pragma unroll
;                     for (int n = 0; n < 2; ++n) { const unsigned hx = hq[2 * n], hy = hq[2 * n + 1]; const f32x4 a = acc[ai][bj][m][n];
;                         const float v0 = __builtin_fmaf(a[0], scale, __uint_as_float(hx << 16)), v1 = __builtin_fmaf(a[1], scale, __uint_as_float(hx & 0xffff0000u));
;                         const float v2 = __builtin_fmaf(a[2], scale, __uint_as_float(hy << 16)), v3 = __builtin_fmaf(a[3], scale, __uint_as_float(hy & 0xffff0000u));
;                         const unsigned wx = cvt_pk_bf16(v0, v1), wy = cvt_pk_bf16(v2, v3); wq[2 * n] = wx; wq[2 * n + 1] = wy;
;                         const float r0 = __uint_as_float(wx << 16), r1 = __uint_as_float(wx & 0xffff0000u), r2 = __uint_as_float(wy << 16), r3 = __uint_as_float(wy & 0xffff0000u);
;                         s += (r0 * r0 + r1 * r1) + (r2 * r2 + r3 * r3); }
;                     *(u32x4*)(HB + off + bj * HALF) = (u32x4){wq[0], wq[1], wq[2], wq[3]}; }
;                 s += __shfl_xor(s, 16); s += __shfl_xor(s, 32);
;                 if (fq == 0) red[(ai * HALF + wr * 64 + m * 16 + fr) * 4 + wc] = s; }
.LBB0_603:
	v_cmp_lt_i32_e32 vcc, v196, v234
	s_waitcnt vmcnt(0)
	v_lshlrev_b32_e32 v197, 16, v236
	v_fmac_f32_e32 v197, s24, v180
	v_and_b32_e32 v180, 0xffff0000, v236
	v_fmac_f32_e32 v180, s24, v181
	v_lshlrev_b32_e32 v181, 16, v237
	v_fmac_f32_e32 v181, s24, v182
	v_and_b32_e32 v182, 0xffff0000, v237
	v_fmac_f32_e32 v182, s24, v183
	v_cvt_pk_bf16_f32 v180, v197, v180
	v_cvt_pk_bf16_f32 v181, v181, v182
	s_nop 0
	v_and_b32_e32 v183, 0xffff0000, v180
	v_lshlrev_b32_e32 v182, 16, v180
	v_and_b32_e32 v236, 0xffff0000, v181
	v_mul_f32_e32 v183, v183, v183
	v_lshlrev_b32_e32 v197, 16, v181
	v_fmac_f32_e32 v183, v182, v182
	v_mul_f32_e32 v182, v236, v236
	v_fmac_f32_e32 v182, v197, v197
	v_add_f32_e32 v197, v183, v182
	v_lshlrev_b32_e32 v182, 16, v238
	v_fmac_f32_e32 v182, s24, v172
	v_and_b32_e32 v172, 0xffff0000, v238
	v_fmac_f32_e32 v172, s24, v173
	v_lshlrev_b32_e32 v173, 16, v239
	v_fmac_f32_e32 v173, s24, v174
	v_and_b32_e32 v174, 0xffff0000, v239
	v_fmac_f32_e32 v174, s24, v175
	v_cvt_pk_bf16_f32 v182, v182, v172
	v_cvt_pk_bf16_f32 v183, v173, v174
	s_nop 0
	v_and_b32_e32 v173, 0xffff0000, v182
	v_lshlrev_b32_e32 v172, 16, v182
	v_and_b32_e32 v175, 0xffff0000, v183
	v_mul_f32_e32 v173, v173, v173
	v_lshlrev_b32_e32 v174, 16, v183
	v_fmac_f32_e32 v173, v172, v172
	v_mul_f32_e32 v172, v175, v175
	v_fmac_f32_e32 v172, v174, v174
	v_lshlrev_b32_e32 v175, 16, v192
	v_add_f32_e32 v172, v173, v172
	v_fmac_f32_e32 v175, s24, v128
	v_and_b32_e32 v128, 0xffff0000, v192
	v_add_f32_e32 v174, v197, v172
	v_lshl_add_u64 v[172:173], s[30:31], 0, v[226:227]
	v_fmac_f32_e32 v128, s24, v129
	v_lshlrev_b32_e32 v129, 16, v193
	v_lshl_add_u64 v[172:173], v[172:173], 0, v[224:225]
	v_fmac_f32_e32 v129, s24, v130
	v_and_b32_e32 v130, 0xffff0000, v193
	global_store_dwordx4 v[172:173], v[180:183], off
	v_fmac_f32_e32 v130, s24, v131
	v_cvt_pk_bf16_f32 v128, v175, v128
	v_cvt_pk_bf16_f32 v129, v129, v130
	s_nop 0
	v_and_b32_e32 v131, 0xffff0000, v128
	v_lshlrev_b32_e32 v130, 16, v128
	v_and_b32_e32 v180, 0xffff0000, v129
	v_mul_f32_e32 v131, v131, v131
	v_lshlrev_b32_e32 v175, 16, v129
	v_fmac_f32_e32 v131, v130, v130
	v_mul_f32_e32 v130, v180, v180
	v_fmac_f32_e32 v130, v175, v175
	v_add_f32_e32 v130, v131, v130
	v_add_f32_e32 v174, v174, v130
	v_lshlrev_b32_e32 v130, 16, v194
	v_fmac_f32_e32 v130, s24, v124
	v_and_b32_e32 v124, 0xffff0000, v194
	v_fmac_f32_e32 v124, s24, v125
	v_lshlrev_b32_e32 v125, 16, v195
	v_fmac_f32_e32 v125, s24, v126
	v_and_b32_e32 v126, 0xffff0000, v195
	v_fmac_f32_e32 v126, s24, v127
	v_cvt_pk_bf16_f32 v130, v130, v124
	v_cvt_pk_bf16_f32 v131, v125, v126
	global_store_dwordx4 v[172:173], v[128:131], off offset:256
	v_and_b32_e32 v125, 0xffff0000, v130
	v_lshlrev_b32_e32 v124, 16, v130
	v_and_b32_e32 v127, 0xffff0000, v131
	v_mul_f32_e32 v125, v125, v125
	v_lshlrev_b32_e32 v126, 16, v131
	v_fmac_f32_e32 v125, v124, v124
	v_mul_f32_e32 v124, v127, v127
	v_fmac_f32_e32 v124, v126, v126
	v_add_f32_e32 v124, v125, v124
	v_add_f32_e32 v125, v174, v124
	v_cndmask_b32_e32 v124, v232, v196, vcc
	v_lshlrev_b32_e32 v124, 2, v124
	ds_bpermute_b32 v126, v124, v125
	v_cmp_lt_i32_e32 vcc, v240, v234
	s_waitcnt lgkmcnt(0)
	v_add_f32_e32 v126, v125, v126
	v_cndmask_b32_e32 v125, v232, v240, vcc
	v_lshlrev_b32_e32 v125, 2, v125
	ds_bpermute_b32 v127, v125, v126
	s_and_saveexec_b64 s[46:47], s[40:41]
	s_cbranch_execz .LBB0_605
	s_waitcnt lgkmcnt(0)
	v_add_f32_e32 v126, v126, v127
	ds_write_b32 v246, v126
